# GQA fast-loop body rescheduled (K frags preloaded, exp/cvt interleaved with MFMAs, extra frag buffers v204-v231) + HGRN barrier vmcnt drains removed
# baseline (speedup 1.0000x reference)
; #define MFMA32(a, b, c) __builtin_amdgcn_mfma_f32_32x32x16_bf16((a), (b), (c), 0, 0, 0)
; DI float fadd1(float a, float b) { float r; asm("v_add_f32 %0, %1, %2" : "=v"(r) : "v"(a), "v"(b)); return r; }
; template <int NKS>
; DI void attn_tile(const Params& p, int layer, int seq, int slot, int qt, char* smem, bool wr = true) {
;     ...
;       auto kb_body = [&](int kb) {
;         bf16x8 kf[NKS];
; #pragma unroll
;         for (int ks = 0; ks < NKS; ++ks) kf[ks] = *(const bf16x8*)(sK + swz(32 * kb + r, 2 * (ks0 + ks) + h));
;         bf16x8 pk[2][2];
; #pragma unroll
;         for (int qb = 0; qb < 2; ++qb) {
;           f32x16 st;
; #pragma unroll
;           for (int i = 0; i < 16; ++i) st[i] = SUB ? ncb[qb] : 0.f;
; #pragma unroll
;           for (int ks = 0; ks < NKS; ++ks) st = MFMA32(kf[ks], qf[qb][ks], st);
;           if constexpr (SUB) {
;             float ls = 0.f;
; #pragma unroll
;             for (int i = 0; i < 16; ++i) { float e = __builtin_amdgcn_exp2f(st[i]); st[i] = e; ls = fadd1(ls, e); }
;             lsum[qb] += ls;
;             pk[qb][0] = pack8(st, 0); pk[qb][1] = pack8(st, 1);
;           } else {
; #pragma unroll
;             for (int i = 0; i < 16; ++i) st[i] = __builtin_amdgcn_exp2f(st[i]);
;             pk[qb][0] = pack8(st, 0); pk[qb][1] = pack8(st, 1);
;             ls4[qb] = __builtin_amdgcn_mfma_f32_16x16x32_bf16(selA, pk[qb][0], ls4[qb], 0, 0, 0);
;             ls4[qb] = __builtin_amdgcn_mfma_f32_16x16x32_bf16(selA, pk[qb][1], ls4[qb], 0, 0, 0);
;           }
;         }
; #pragma unroll
;         for (int eb = 0; eb < 2; ++eb)
; #pragma unroll
;           for (int s2 = 0; s2 < 2; ++s2) {
;             bf16x8 vf = *(const bf16x8*)(sV + swz(32 * eb + r, 4 * kb + 2 * s2 + h));
; #pragma unroll
;             for (int qb = 0; qb < 2; ++qb) O[qb][eb] = MFMA32(vf, pk[qb][s2], O[qb][eb]);
;           }
;       };
.LBB0_640:
	s_add_i32 s15, s14, s15
	v_lshl_add_u32 v128, v187, 1, s15
	v_lshl_add_u32 v130, v188, 1, s15
	v_lshl_add_u32 v131, v189, 1, s15
	v_lshl_add_u32 v191, v190, 1, s15
	ds_read_b128 v[192:195], v128
	ds_read_b128 v[196:199], v130
	ds_read_b128 v[200:203], v131
	ds_read_b128 v[204:207], v191
	ds_read_b128 v[208:211], v128 offset:4096
	ds_read_b128 v[212:215], v130 offset:4096
	ds_read_b128 v[216:219], v131 offset:4096
	ds_read_b128 v[220:223], v191 offset:4096
	ds_read_b128 v[224:227], v128 offset:16384
	ds_read_b128 v[228:231], v128 offset:20480
	s_movk_i32 s15, 0x2000
	s_andn2_b64 vcc, exec, s[4:5]
	s_mov_b64 s[4:5], 0
	s_waitcnt lgkmcnt(9)
	v_mfma_f32_32x32x16_bf16 v[112:127], v[192:195], v[132:135], 0
	s_waitcnt lgkmcnt(8)
	v_mfma_f32_32x32x16_bf16 v[112:127], v[196:199], v[136:139], v[112:127]
	s_waitcnt lgkmcnt(7)
	v_mfma_f32_32x32x16_bf16 v[112:127], v[200:203], v[140:143], v[112:127]
	s_waitcnt lgkmcnt(6)
	v_mfma_f32_32x32x16_bf16 v[112:127], v[204:207], v[144:147], v[112:127]
	v_mfma_f32_32x32x16_bf16 v[96:111], v[192:195], v[148:151], 0
	v_mfma_f32_32x32x16_bf16 v[96:111], v[196:199], v[152:155], v[96:111]
	v_mfma_f32_32x32x16_bf16 v[96:111], v[200:203], v[156:159], v[96:111]
	v_mfma_f32_32x32x16_bf16 v[96:111], v[204:207], v[160:163], v[96:111]
	ds_read_b128 v[192:195], v130 offset:16384
	ds_read_b128 v[196:199], v130 offset:20480
	ds_read_b128 v[200:203], v131 offset:16384
	ds_read_b128 v[204:207], v131 offset:20480
	s_waitcnt lgkmcnt(9)
	v_mfma_f32_32x32x16_bf16 v[64:79], v[208:211], v[132:135], 0
	s_nop 1
	v_exp_f32_e32 v112, v112
	v_exp_f32_e32 v113, v113
	v_exp_f32_e32 v114, v114
	v_exp_f32_e32 v115, v115
	v_cvt_pk_bf16_f32 v112, v112, v113
	v_cvt_pk_bf16_f32 v113, v114, v115
	s_waitcnt lgkmcnt(8)
	v_mfma_f32_32x32x16_bf16 v[64:79], v[212:215], v[136:139], v[64:79]
	v_exp_f32_e32 v116, v116
	v_exp_f32_e32 v117, v117
	v_exp_f32_e32 v118, v118
	v_exp_f32_e32 v119, v119
	v_cvt_pk_bf16_f32 v114, v116, v117
	v_cvt_pk_bf16_f32 v115, v118, v119
	s_waitcnt lgkmcnt(7)
	v_mfma_f32_32x32x16_bf16 v[64:79], v[216:219], v[140:143], v[64:79]
	v_exp_f32_e32 v120, v120
	v_exp_f32_e32 v121, v121
	v_exp_f32_e32 v122, v122
	v_exp_f32_e32 v123, v123
	v_cvt_pk_bf16_f32 v116, v120, v121
	v_cvt_pk_bf16_f32 v117, v122, v123
	s_waitcnt lgkmcnt(6)
	v_mfma_f32_32x32x16_bf16 v[64:79], v[220:223], v[144:147], v[64:79]
	s_waitcnt lgkmcnt(5)
	v_mfma_f32_32x32x16_bf16 v[48:63], v[224:227], v[112:115], v[48:63]
	v_exp_f32_e32 v124, v124
	v_exp_f32_e32 v125, v125
	v_exp_f32_e32 v126, v126
	v_exp_f32_e32 v127, v127
	v_cvt_pk_bf16_f32 v118, v124, v125
	v_cvt_pk_bf16_f32 v119, v126, v127
	v_mfma_f32_32x32x16_bf16 v[80:95], v[208:211], v[148:151], 0
	s_waitcnt lgkmcnt(4)
	v_mfma_f32_32x32x16_bf16 v[32:47], v[228:231], v[112:115], v[32:47]
	v_exp_f32_e32 v96, v96
	v_exp_f32_e32 v97, v97
	v_exp_f32_e32 v98, v98
	v_exp_f32_e32 v99, v99
	v_cvt_pk_bf16_f32 v96, v96, v97
	v_cvt_pk_bf16_f32 v97, v98, v99
	v_mfma_f32_16x16x32_bf16 v[164:167], v[172:175], v[112:115], v[164:167]
	v_mfma_f32_32x32x16_bf16 v[80:95], v[212:215], v[152:155], v[80:95]
	v_exp_f32_e32 v100, v100
	v_exp_f32_e32 v101, v101
	v_exp_f32_e32 v102, v102
	v_exp_f32_e32 v103, v103
	v_cvt_pk_bf16_f32 v98, v100, v101
	v_cvt_pk_bf16_f32 v99, v102, v103
	v_mfma_f32_32x32x16_bf16 v[80:95], v[216:219], v[156:159], v[80:95]
	s_waitcnt lgkmcnt(3)
	v_mfma_f32_32x32x16_bf16 v[48:63], v[192:195], v[116:119], v[48:63]
	v_exp_f32_e32 v104, v104
	v_exp_f32_e32 v105, v105
	v_exp_f32_e32 v106, v106
	v_exp_f32_e32 v107, v107
	v_cvt_pk_bf16_f32 v100, v104, v105
	v_cvt_pk_bf16_f32 v101, v106, v107
	s_waitcnt lgkmcnt(2)
	v_mfma_f32_32x32x16_bf16 v[32:47], v[196:199], v[116:119], v[32:47]
	v_mfma_f32_16x16x32_bf16 v[164:167], v[172:175], v[116:119], v[164:167]
	v_exp_f32_e32 v108, v108
	v_exp_f32_e32 v109, v109
	v_exp_f32_e32 v110, v110
	v_exp_f32_e32 v111, v111
	v_cvt_pk_bf16_f32 v102, v108, v109
	v_cvt_pk_bf16_f32 v103, v110, v111
	v_mfma_f32_32x32x16_bf16 v[80:95], v[220:223], v[160:163], v[80:95]
	ds_read_b128 v[208:211], v191 offset:16384
	ds_read_b128 v[212:215], v191 offset:20480
	v_mfma_f32_32x32x16_bf16 v[16:31], v[224:227], v[96:99], v[16:31]
	v_exp_f32_e32 v64, v64
	v_exp_f32_e32 v65, v65
	v_exp_f32_e32 v66, v66
	v_exp_f32_e32 v67, v67
	v_cvt_pk_bf16_f32 v64, v64, v65
	v_cvt_pk_bf16_f32 v65, v66, v67
	v_mfma_f32_32x32x16_bf16 v[0:15], v[228:231], v[96:99], v[0:15]
	v_mfma_f32_16x16x32_bf16 v[168:171], v[172:175], v[96:99], v[168:171]
	v_exp_f32_e32 v68, v68
	v_exp_f32_e32 v69, v69
	v_exp_f32_e32 v70, v70
	v_exp_f32_e32 v71, v71
	v_cvt_pk_bf16_f32 v66, v68, v69
	v_cvt_pk_bf16_f32 v67, v70, v71
	v_mfma_f32_32x32x16_bf16 v[16:31], v[192:195], v[100:103], v[16:31]
	v_mfma_f32_32x32x16_bf16 v[0:15], v[196:199], v[100:103], v[0:15]
	v_exp_f32_e32 v72, v72
	v_exp_f32_e32 v73, v73
	v_exp_f32_e32 v74, v74
	v_exp_f32_e32 v75, v75
	v_cvt_pk_bf16_f32 v68, v72, v73
	v_cvt_pk_bf16_f32 v69, v74, v75
	v_mfma_f32_16x16x32_bf16 v[168:171], v[172:175], v[100:103], v[168:171]
	s_waitcnt lgkmcnt(3)
	v_mfma_f32_32x32x16_bf16 v[48:63], v[200:203], v[64:67], v[48:63]
	v_exp_f32_e32 v76, v76
	v_exp_f32_e32 v77, v77
	v_exp_f32_e32 v78, v78
	v_exp_f32_e32 v79, v79
	v_cvt_pk_bf16_f32 v70, v76, v77
	v_cvt_pk_bf16_f32 v71, v78, v79
	s_waitcnt lgkmcnt(2)
	v_mfma_f32_32x32x16_bf16 v[32:47], v[204:207], v[64:67], v[32:47]
	v_mfma_f32_16x16x32_bf16 v[164:167], v[172:175], v[64:67], v[164:167]
	v_exp_f32_e32 v80, v80
	v_exp_f32_e32 v81, v81
	v_exp_f32_e32 v82, v82
	v_exp_f32_e32 v83, v83
	v_cvt_pk_bf16_f32 v80, v80, v81
	v_cvt_pk_bf16_f32 v81, v82, v83
	s_waitcnt lgkmcnt(1)
	v_mfma_f32_32x32x16_bf16 v[48:63], v[208:211], v[68:71], v[48:63]
	v_exp_f32_e32 v84, v84
	v_exp_f32_e32 v85, v85
	v_exp_f32_e32 v86, v86
	v_exp_f32_e32 v87, v87
	v_cvt_pk_bf16_f32 v82, v84, v85
	v_cvt_pk_bf16_f32 v83, v86, v87
	s_waitcnt lgkmcnt(0)
	v_mfma_f32_32x32x16_bf16 v[32:47], v[212:215], v[68:71], v[32:47]
	v_mfma_f32_16x16x32_bf16 v[164:167], v[172:175], v[68:71], v[164:167]
	v_exp_f32_e32 v88, v88
	v_exp_f32_e32 v89, v89
	v_exp_f32_e32 v90, v90
	v_exp_f32_e32 v91, v91
	v_cvt_pk_bf16_f32 v84, v88, v89
	v_cvt_pk_bf16_f32 v85, v90, v91
	v_mfma_f32_32x32x16_bf16 v[16:31], v[200:203], v[80:83], v[16:31]
	v_exp_f32_e32 v92, v92
	v_exp_f32_e32 v93, v93
	v_exp_f32_e32 v94, v94
	v_exp_f32_e32 v95, v95
	v_cvt_pk_bf16_f32 v86, v92, v93
	v_cvt_pk_bf16_f32 v87, v94, v95
	v_mfma_f32_32x32x16_bf16 v[0:15], v[204:207], v[80:83], v[0:15]
	v_mfma_f32_16x16x32_bf16 v[168:171], v[172:175], v[80:83], v[168:171]
	v_mfma_f32_32x32x16_bf16 v[16:31], v[208:211], v[84:87], v[16:31]
	v_mfma_f32_32x32x16_bf16 v[0:15], v[212:215], v[84:87], v[0:15]
	v_mfma_f32_16x16x32_bf16 v[168:171], v[172:175], v[84:87], v[168:171]
	s_cbranch_vccz .LBB0_640
	s_cmp_eq_u32 s28, s25
	s_cbranch_scc1 .LBB0_643
	s_mov_b32 s29, s28
	s_branch .LBB0_637
